# u sweep compute batched per half sub-step: 8+8 fp8 MFMAs back to back, one exec-masked add/pack section with ds_read2/ds_write2 instead of eight serial MFMA->DPP->branch->LDS round trips
# speedup vs baseline: 1.0014x; 1.0004x over previous
.LBB0_1073:
	s_mov_b32 s4, s3
	s_lshr_b32 s3, s3, 5
	s_lshl_b32 s18, s3, 21
	v_lshl_add_u64 v[16:17], v[78:79], 0, s[18:19]
	s_waitcnt lgkmcnt(7)
	v_lshlrev_b32_sdwa v72, v141, v72 dst_sel:DWORD dst_unused:UNUSED_PAD src0_sel:DWORD src1_sel:WORD_0
	v_lshl_add_u64 v[18:19], v[16:17], 0, v[72:73]
	s_waitcnt lgkmcnt(6)
	v_lshlrev_b32_sdwa v72, v141, v96 dst_sel:DWORD dst_unused:UNUSED_PAD src0_sel:DWORD src1_sel:WORD_0
	v_lshl_add_u64 v[20:21], v[16:17], 0, v[72:73]
	s_waitcnt lgkmcnt(5)
	v_lshlrev_b32_sdwa v72, v141, v95 dst_sel:DWORD dst_unused:UNUSED_PAD src0_sel:DWORD src1_sel:WORD_0
	global_load_dwordx4 v[68:71], v[18:19], off
	global_load_dwordx4 v[64:67], v[20:21], off
	v_lshl_add_u64 v[18:19], v[16:17], 0, v[72:73]
	s_waitcnt lgkmcnt(4)
	v_lshlrev_b32_sdwa v72, v141, v94 dst_sel:DWORD dst_unused:UNUSED_PAD src0_sel:DWORD src1_sel:WORD_0
	v_lshl_add_u64 v[20:21], v[16:17], 0, v[72:73]
	s_waitcnt lgkmcnt(3)
	v_lshlrev_b32_sdwa v72, v141, v93 dst_sel:DWORD dst_unused:UNUSED_PAD src0_sel:DWORD src1_sel:WORD_0
	global_load_dwordx4 v[60:63], v[18:19], off
	global_load_dwordx4 v[52:55], v[20:21], off
	v_lshl_add_u64 v[18:19], v[16:17], 0, v[72:73]
	s_waitcnt lgkmcnt(2)
	v_lshlrev_b32_sdwa v72, v141, v92 dst_sel:DWORD dst_unused:UNUSED_PAD src0_sel:DWORD src1_sel:WORD_0
	s_and_b32 s5, s4, 31
	v_lshl_add_u64 v[20:21], v[16:17], 0, v[72:73]
	s_waitcnt lgkmcnt(1)
	v_lshlrev_b32_sdwa v72, v141, v91 dst_sel:DWORD dst_unused:UNUSED_PAD src0_sel:DWORD src1_sel:WORD_0
	s_lshl_b32 s18, s5, 10
	global_load_dwordx4 v[44:47], v[18:19], off
	global_load_dwordx4 v[36:39], v[20:21], off
	v_lshl_add_u64 v[18:19], v[16:17], 0, v[72:73]
	s_waitcnt lgkmcnt(0)
	v_lshlrev_b32_sdwa v72, v141, v90 dst_sel:DWORD dst_unused:UNUSED_PAD src0_sel:DWORD src1_sel:WORD_0
	v_lshl_add_u64 v[20:21], v[80:81], 0, s[18:19]
	s_lshl_b32 s18, s3, 7
	v_lshl_add_u64 v[16:17], v[16:17], 0, v[72:73]
	v_lshl_add_u64 v[20:21], v[20:21], 0, s[18:19]
	global_load_dwordx4 v[28:31], v[18:19], off
	s_nop 0
	global_load_dwordx4 v[16:19], v[16:17], off
	s_add_i32 s3, s4, 1
	global_load_dwordx4 v[20:23], v[20:21], off
	s_and_b32 s39, s3, 31
	s_lshl_b32 s11, s39, 8
	v_add_u32_e32 v90, s11, v88
	ds_read_u16 v72, v90
	ds_read_u16 v97, v90 offset:16
	ds_read_u16 v96, v90 offset:32
	ds_read_u16 v95, v90 offset:48
	ds_read_u16 v94, v90 offset:64
	ds_read_u16 v93, v90 offset:80
	ds_read_u16 v92, v90 offset:96
	ds_read_u16 v91, v90 offset:112
	s_waitcnt vmcnt(9)
	v_mfma_f32_16x16x32_fp8_fp8 v[102:105], v[56:57], v[4:5], 0
	s_lshl_b32 s11, s5, 8
	s_cmp_gt_u32 s4, 31
	s_cselect_b32 s98, 1, 0
	v_mfma_f32_16x16x32_fp8_fp8 v[106:109], v[48:49], v[4:5], 0
	v_mfma_f32_16x16x32_fp8_fp8 v[110:113], v[40:41], v[4:5], 0
	v_mfma_f32_16x16x32_fp8_fp8 v[114:117], v[32:33], v[4:5], 0
	v_mfma_f32_16x16x32_fp8_fp8 v[118:121], v[24:25], v[4:5], 0
	v_mfma_f32_16x16x32_fp8_fp8 v[122:125], v[12:13], v[4:5], 0
	v_mfma_f32_16x16x32_fp8_fp8 v[126:129], v[8:9], v[4:5], 0
	v_mfma_f32_16x16x32_fp8_fp8 v[130:133], v[0:1], v[4:5], 0
	v_mfma_f32_16x16x32_fp8_fp8 v[56:59], v[58:59], v[6:7], v[102:105]
	v_mfma_f32_16x16x32_fp8_fp8 v[48:51], v[50:51], v[6:7], v[106:109]
	v_mfma_f32_16x16x32_fp8_fp8 v[40:43], v[42:43], v[6:7], v[110:113]
	v_mfma_f32_16x16x32_fp8_fp8 v[32:35], v[34:35], v[6:7], v[114:117]
	v_mfma_f32_16x16x32_fp8_fp8 v[24:27], v[26:27], v[6:7], v[118:121]
	v_mfma_f32_16x16x32_fp8_fp8 v[12:15], v[14:15], v[6:7], v[122:125]
	v_mfma_f32_16x16x32_fp8_fp8 v[8:11], v[10:11], v[6:7], v[126:129]
	v_mfma_f32_16x16x32_fp8_fp8 v[0:3], v[2:3], v[6:7], v[130:133]
	v_add_u32_e32 v134, s11, v89
	s_nop 7
	v_mov_b32_dpp v102, v57 quad_perm:[1,0,3,2] row_mask:0xf bank_mask:0xf bound_ctrl:1
	v_mov_b32_dpp v103, v59 quad_perm:[1,0,3,2] row_mask:0xf bank_mask:0xf bound_ctrl:1
	v_mov_b32_dpp v106, v49 quad_perm:[1,0,3,2] row_mask:0xf bank_mask:0xf bound_ctrl:1
	v_mov_b32_dpp v107, v51 quad_perm:[1,0,3,2] row_mask:0xf bank_mask:0xf bound_ctrl:1
	v_mov_b32_dpp v110, v41 quad_perm:[1,0,3,2] row_mask:0xf bank_mask:0xf bound_ctrl:1
	v_mov_b32_dpp v111, v43 quad_perm:[1,0,3,2] row_mask:0xf bank_mask:0xf bound_ctrl:1
	v_mov_b32_dpp v114, v33 quad_perm:[1,0,3,2] row_mask:0xf bank_mask:0xf bound_ctrl:1
	v_mov_b32_dpp v115, v35 quad_perm:[1,0,3,2] row_mask:0xf bank_mask:0xf bound_ctrl:1
	v_mov_b32_dpp v118, v25 quad_perm:[1,0,3,2] row_mask:0xf bank_mask:0xf bound_ctrl:1
	v_mov_b32_dpp v119, v27 quad_perm:[1,0,3,2] row_mask:0xf bank_mask:0xf bound_ctrl:1
	v_mov_b32_dpp v122, v13 quad_perm:[1,0,3,2] row_mask:0xf bank_mask:0xf bound_ctrl:1
	v_mov_b32_dpp v123, v15 quad_perm:[1,0,3,2] row_mask:0xf bank_mask:0xf bound_ctrl:1
	v_mov_b32_dpp v126, v9 quad_perm:[1,0,3,2] row_mask:0xf bank_mask:0xf bound_ctrl:1
	v_mov_b32_dpp v127, v11 quad_perm:[1,0,3,2] row_mask:0xf bank_mask:0xf bound_ctrl:1
	v_mov_b32_dpp v130, v1 quad_perm:[1,0,3,2] row_mask:0xf bank_mask:0xf bound_ctrl:1
	v_mov_b32_dpp v131, v3 quad_perm:[1,0,3,2] row_mask:0xf bank_mask:0xf bound_ctrl:1
	s_and_saveexec_b64 s[62:63], s[0:1]
	s_cmp_eq_u32 s98, 0
	s_cbranch_scc1 .Lu0_first
	ds_read2_b32 v[104:105], v134 offset0:0 offset1:4
	ds_read2_b32 v[112:113], v134 offset0:8 offset1:12
	ds_read2_b32 v[120:121], v134 offset0:16 offset1:20
	ds_read2_b32 v[128:129], v134 offset0:24 offset1:28
	v_mov_b32_e32 v57, v58
	v_mov_b32_e32 v49, v50
	v_mov_b32_e32 v41, v42
	v_mov_b32_e32 v33, v34
	v_mov_b32_e32 v25, v26
	v_mov_b32_e32 v13, v14
	v_mov_b32_e32 v9, v10
	v_mov_b32_e32 v1, v2
	v_pk_add_f32 v[56:57], v[56:57], v[102:103]
	v_pk_add_f32 v[48:49], v[48:49], v[106:107]
	v_pk_add_f32 v[40:41], v[40:41], v[110:111]
	v_pk_add_f32 v[32:33], v[32:33], v[114:115]
	v_pk_add_f32 v[24:25], v[24:25], v[118:119]
	v_pk_add_f32 v[12:13], v[12:13], v[122:123]
	v_pk_add_f32 v[8:9], v[8:9], v[126:127]
	v_pk_add_f32 v[0:1], v[0:1], v[130:131]
	s_waitcnt lgkmcnt(0)
	v_lshlrev_b32_e32 v102, 16, v104
	v_and_b32_e32 v103, 0xffff0000, v104
	v_lshlrev_b32_e32 v106, 16, v105
	v_and_b32_e32 v107, 0xffff0000, v105
	v_lshlrev_b32_e32 v110, 16, v112
	v_and_b32_e32 v111, 0xffff0000, v112
	v_lshlrev_b32_e32 v114, 16, v113
	v_and_b32_e32 v115, 0xffff0000, v113
	v_lshlrev_b32_e32 v118, 16, v120
	v_and_b32_e32 v119, 0xffff0000, v120
	v_lshlrev_b32_e32 v122, 16, v121
	v_and_b32_e32 v123, 0xffff0000, v121
	v_lshlrev_b32_e32 v126, 16, v128
	v_and_b32_e32 v127, 0xffff0000, v128
	v_lshlrev_b32_e32 v130, 16, v129
	v_and_b32_e32 v131, 0xffff0000, v129
	v_pk_add_f32 v[56:57], v[56:57], v[102:103]
	v_pk_add_f32 v[48:49], v[48:49], v[106:107]
	v_pk_add_f32 v[40:41], v[40:41], v[110:111]
	v_pk_add_f32 v[32:33], v[32:33], v[114:115]
	v_pk_add_f32 v[24:25], v[24:25], v[118:119]
	v_pk_add_f32 v[12:13], v[12:13], v[122:123]
	v_pk_add_f32 v[8:9], v[8:9], v[126:127]
	v_pk_add_f32 v[0:1], v[0:1], v[130:131]
	s_branch .Lu0_pack
.Lu0_first:
	v_mov_b32_e32 v57, v58
	v_mov_b32_e32 v49, v50
	v_mov_b32_e32 v41, v42
	v_mov_b32_e32 v33, v34
	v_mov_b32_e32 v25, v26
	v_mov_b32_e32 v13, v14
	v_mov_b32_e32 v9, v10
	v_mov_b32_e32 v1, v2
	v_pk_add_f32 v[56:57], v[56:57], v[102:103]
	v_pk_add_f32 v[48:49], v[48:49], v[106:107]
	v_pk_add_f32 v[40:41], v[40:41], v[110:111]
	v_pk_add_f32 v[32:33], v[32:33], v[114:115]
	v_pk_add_f32 v[24:25], v[24:25], v[118:119]
	v_pk_add_f32 v[12:13], v[12:13], v[122:123]
	v_pk_add_f32 v[8:9], v[8:9], v[126:127]
	v_pk_add_f32 v[0:1], v[0:1], v[130:131]
.Lu0_pack:
	s_nop 0
	v_cvt_pk_bf16_f32 v56, v56, v57
	v_cvt_pk_bf16_f32 v48, v48, v49
	v_cvt_pk_bf16_f32 v40, v40, v41
	v_cvt_pk_bf16_f32 v32, v32, v33
	v_cvt_pk_bf16_f32 v24, v24, v25
	v_cvt_pk_bf16_f32 v12, v12, v13
	v_cvt_pk_bf16_f32 v8, v8, v9
	v_cvt_pk_bf16_f32 v0, v0, v1
	ds_write2_b32 v134, v56, v48 offset0:0 offset1:4
	ds_write2_b32 v134, v40, v32 offset0:8 offset1:12
	ds_write2_b32 v134, v24, v12 offset0:16 offset1:20
	ds_write2_b32 v134, v8, v0 offset0:24 offset1:28
	s_or_b64 exec, exec, s[62:63]
	s_bfe_u32 s41, s3, 0x30005
	s_lshl_b32 s18, s41, 21
	v_lshl_add_u64 v[0:1], v[78:79], 0, s[18:19]
	s_waitcnt lgkmcnt(7)
	v_lshlrev_b32_sdwa v72, v141, v72 dst_sel:DWORD dst_unused:UNUSED_PAD src0_sel:DWORD src1_sel:WORD_0
	v_lshl_add_u64 v[2:3], v[0:1], 0, v[72:73]
	s_waitcnt lgkmcnt(6)
	v_lshlrev_b32_sdwa v72, v141, v97 dst_sel:DWORD dst_unused:UNUSED_PAD src0_sel:DWORD src1_sel:WORD_0
	v_lshl_add_u64 v[4:5], v[0:1], 0, v[72:73]
	s_waitcnt lgkmcnt(5)
	v_lshlrev_b32_sdwa v72, v141, v96 dst_sel:DWORD dst_unused:UNUSED_PAD src0_sel:DWORD src1_sel:WORD_0
	global_load_dwordx4 v[56:59], v[2:3], off
	global_load_dwordx4 v[48:51], v[4:5], off
	v_lshl_add_u64 v[2:3], v[0:1], 0, v[72:73]
	s_waitcnt lgkmcnt(4)
	v_lshlrev_b32_sdwa v72, v141, v95 dst_sel:DWORD dst_unused:UNUSED_PAD src0_sel:DWORD src1_sel:WORD_0
	v_lshl_add_u64 v[4:5], v[0:1], 0, v[72:73]
	s_waitcnt lgkmcnt(3)
	v_lshlrev_b32_sdwa v72, v141, v94 dst_sel:DWORD dst_unused:UNUSED_PAD src0_sel:DWORD src1_sel:WORD_0
	global_load_dwordx4 v[40:43], v[2:3], off
	global_load_dwordx4 v[32:35], v[4:5], off
	v_lshl_add_u64 v[2:3], v[0:1], 0, v[72:73]
	s_waitcnt lgkmcnt(2)
	v_lshlrev_b32_sdwa v72, v141, v93 dst_sel:DWORD dst_unused:UNUSED_PAD src0_sel:DWORD src1_sel:WORD_0
	v_lshl_add_u64 v[4:5], v[0:1], 0, v[72:73]
	s_waitcnt lgkmcnt(1)
	v_lshlrev_b32_sdwa v72, v141, v92 dst_sel:DWORD dst_unused:UNUSED_PAD src0_sel:DWORD src1_sel:WORD_0
	s_lshl_b32 s18, s39, 10
	global_load_dwordx4 v[24:27], v[2:3], off
	global_load_dwordx4 v[12:15], v[4:5], off
	v_lshl_add_u64 v[2:3], v[0:1], 0, v[72:73]
	s_waitcnt lgkmcnt(0)
	v_lshlrev_b32_sdwa v72, v141, v91 dst_sel:DWORD dst_unused:UNUSED_PAD src0_sel:DWORD src1_sel:WORD_0
	v_lshl_add_u64 v[4:5], v[80:81], 0, s[18:19]
	s_lshl_b32 s18, s41, 7
	v_lshl_add_u64 v[0:1], v[0:1], 0, v[72:73]
	v_lshl_add_u64 v[4:5], v[4:5], 0, s[18:19]
	global_load_dwordx4 v[8:11], v[2:3], off
	s_nop 0
	global_load_dwordx4 v[0:3], v[0:1], off
	s_waitcnt vmcnt(8)
	v_mfma_f32_16x16x32_fp8_fp8 v[102:105], v[68:69], v[20:21], 0
	global_load_dwordx4 v[4:7], v[4:5], off
	ds_read_u16 v72, v90 offset:128
	ds_read_u16 v96, v90 offset:144
	ds_read_u16 v95, v90 offset:160
	ds_read_u16 v94, v90 offset:176
	ds_read_u16 v93, v90 offset:192
	ds_read_u16 v92, v90 offset:208
	ds_read_u16 v91, v90 offset:224
	ds_read_u16 v90, v90 offset:240
	v_mfma_f32_16x16x32_fp8_fp8 v[106:109], v[64:65], v[20:21], 0
	v_mfma_f32_16x16x32_fp8_fp8 v[110:113], v[60:61], v[20:21], 0
	v_mfma_f32_16x16x32_fp8_fp8 v[114:117], v[52:53], v[20:21], 0
	v_mfma_f32_16x16x32_fp8_fp8 v[118:121], v[44:45], v[20:21], 0
	v_mfma_f32_16x16x32_fp8_fp8 v[122:125], v[36:37], v[20:21], 0
	v_mfma_f32_16x16x32_fp8_fp8 v[126:129], v[28:29], v[20:21], 0
	v_mfma_f32_16x16x32_fp8_fp8 v[130:133], v[16:17], v[20:21], 0
	v_mfma_f32_16x16x32_fp8_fp8 v[68:71], v[70:71], v[22:23], v[102:105]
	v_mfma_f32_16x16x32_fp8_fp8 v[64:67], v[66:67], v[22:23], v[106:109]
	v_mfma_f32_16x16x32_fp8_fp8 v[60:63], v[62:63], v[22:23], v[110:113]
	v_mfma_f32_16x16x32_fp8_fp8 v[52:55], v[54:55], v[22:23], v[114:117]
	v_mfma_f32_16x16x32_fp8_fp8 v[44:47], v[46:47], v[22:23], v[118:121]
	v_mfma_f32_16x16x32_fp8_fp8 v[36:39], v[38:39], v[22:23], v[122:125]
	v_mfma_f32_16x16x32_fp8_fp8 v[28:31], v[30:31], v[22:23], v[126:129]
	v_mfma_f32_16x16x32_fp8_fp8 v[16:19], v[18:19], v[22:23], v[130:133]
	v_add_u32_e32 v134, s11, v89
	s_nop 7
	v_mov_b32_dpp v102, v69 quad_perm:[1,0,3,2] row_mask:0xf bank_mask:0xf bound_ctrl:1
	v_mov_b32_dpp v103, v71 quad_perm:[1,0,3,2] row_mask:0xf bank_mask:0xf bound_ctrl:1
	v_mov_b32_dpp v106, v65 quad_perm:[1,0,3,2] row_mask:0xf bank_mask:0xf bound_ctrl:1
	v_mov_b32_dpp v107, v67 quad_perm:[1,0,3,2] row_mask:0xf bank_mask:0xf bound_ctrl:1
	v_mov_b32_dpp v110, v61 quad_perm:[1,0,3,2] row_mask:0xf bank_mask:0xf bound_ctrl:1
	v_mov_b32_dpp v111, v63 quad_perm:[1,0,3,2] row_mask:0xf bank_mask:0xf bound_ctrl:1
	v_mov_b32_dpp v114, v53 quad_perm:[1,0,3,2] row_mask:0xf bank_mask:0xf bound_ctrl:1
	v_mov_b32_dpp v115, v55 quad_perm:[1,0,3,2] row_mask:0xf bank_mask:0xf bound_ctrl:1
	v_mov_b32_dpp v118, v45 quad_perm:[1,0,3,2] row_mask:0xf bank_mask:0xf bound_ctrl:1
	v_mov_b32_dpp v119, v47 quad_perm:[1,0,3,2] row_mask:0xf bank_mask:0xf bound_ctrl:1
	v_mov_b32_dpp v122, v37 quad_perm:[1,0,3,2] row_mask:0xf bank_mask:0xf bound_ctrl:1
	v_mov_b32_dpp v123, v39 quad_perm:[1,0,3,2] row_mask:0xf bank_mask:0xf bound_ctrl:1
	v_mov_b32_dpp v126, v29 quad_perm:[1,0,3,2] row_mask:0xf bank_mask:0xf bound_ctrl:1
	v_mov_b32_dpp v127, v31 quad_perm:[1,0,3,2] row_mask:0xf bank_mask:0xf bound_ctrl:1
	v_mov_b32_dpp v130, v17 quad_perm:[1,0,3,2] row_mask:0xf bank_mask:0xf bound_ctrl:1
	v_mov_b32_dpp v131, v19 quad_perm:[1,0,3,2] row_mask:0xf bank_mask:0xf bound_ctrl:1
	s_and_saveexec_b64 s[62:63], s[0:1]
	s_cmp_eq_u32 s98, 0
	s_cbranch_scc1 .Lu1_first
	ds_read2_b32 v[104:105], v134 offset0:32 offset1:36
	ds_read2_b32 v[112:113], v134 offset0:40 offset1:44
	ds_read2_b32 v[120:121], v134 offset0:48 offset1:52
	ds_read2_b32 v[128:129], v134 offset0:56 offset1:60
	v_mov_b32_e32 v69, v70
	v_mov_b32_e32 v65, v66
	v_mov_b32_e32 v61, v62
	v_mov_b32_e32 v53, v54
	v_mov_b32_e32 v45, v46
	v_mov_b32_e32 v37, v38
	v_mov_b32_e32 v29, v30
	v_mov_b32_e32 v17, v18
	v_pk_add_f32 v[68:69], v[68:69], v[102:103]
	v_pk_add_f32 v[64:65], v[64:65], v[106:107]
	v_pk_add_f32 v[60:61], v[60:61], v[110:111]
	v_pk_add_f32 v[52:53], v[52:53], v[114:115]
	v_pk_add_f32 v[44:45], v[44:45], v[118:119]
	v_pk_add_f32 v[36:37], v[36:37], v[122:123]
	v_pk_add_f32 v[28:29], v[28:29], v[126:127]
	v_pk_add_f32 v[16:17], v[16:17], v[130:131]
	s_waitcnt lgkmcnt(0)
	v_lshlrev_b32_e32 v102, 16, v104
	v_and_b32_e32 v103, 0xffff0000, v104
	v_lshlrev_b32_e32 v106, 16, v105
	v_and_b32_e32 v107, 0xffff0000, v105
	v_lshlrev_b32_e32 v110, 16, v112
	v_and_b32_e32 v111, 0xffff0000, v112
	v_lshlrev_b32_e32 v114, 16, v113
	v_and_b32_e32 v115, 0xffff0000, v113
	v_lshlrev_b32_e32 v118, 16, v120
	v_and_b32_e32 v119, 0xffff0000, v120
	v_lshlrev_b32_e32 v122, 16, v121
	v_and_b32_e32 v123, 0xffff0000, v121
	v_lshlrev_b32_e32 v126, 16, v128
	v_and_b32_e32 v127, 0xffff0000, v128
	v_lshlrev_b32_e32 v130, 16, v129
	v_and_b32_e32 v131, 0xffff0000, v129
	v_pk_add_f32 v[68:69], v[68:69], v[102:103]
	v_pk_add_f32 v[64:65], v[64:65], v[106:107]
	v_pk_add_f32 v[60:61], v[60:61], v[110:111]
	v_pk_add_f32 v[52:53], v[52:53], v[114:115]
	v_pk_add_f32 v[44:45], v[44:45], v[118:119]
	v_pk_add_f32 v[36:37], v[36:37], v[122:123]
	v_pk_add_f32 v[28:29], v[28:29], v[126:127]
	v_pk_add_f32 v[16:17], v[16:17], v[130:131]
	s_branch .Lu1_pack
.Lu1_first:
	v_mov_b32_e32 v69, v70
	v_mov_b32_e32 v65, v66
	v_mov_b32_e32 v61, v62
	v_mov_b32_e32 v53, v54
	v_mov_b32_e32 v45, v46
	v_mov_b32_e32 v37, v38
	v_mov_b32_e32 v29, v30
	v_mov_b32_e32 v17, v18
	v_pk_add_f32 v[68:69], v[68:69], v[102:103]
	v_pk_add_f32 v[64:65], v[64:65], v[106:107]
	v_pk_add_f32 v[60:61], v[60:61], v[110:111]
	v_pk_add_f32 v[52:53], v[52:53], v[114:115]
	v_pk_add_f32 v[44:45], v[44:45], v[118:119]
	v_pk_add_f32 v[36:37], v[36:37], v[122:123]
	v_pk_add_f32 v[28:29], v[28:29], v[126:127]
	v_pk_add_f32 v[16:17], v[16:17], v[130:131]
.Lu1_pack:
	s_nop 0
	v_cvt_pk_bf16_f32 v68, v68, v69
	v_cvt_pk_bf16_f32 v64, v64, v65
	v_cvt_pk_bf16_f32 v60, v60, v61
	v_cvt_pk_bf16_f32 v52, v52, v53
	v_cvt_pk_bf16_f32 v44, v44, v45
	v_cvt_pk_bf16_f32 v36, v36, v37
	v_cvt_pk_bf16_f32 v28, v28, v29
	v_cvt_pk_bf16_f32 v16, v16, v17
	ds_write2_b32 v134, v68, v64 offset0:32 offset1:36
	ds_write2_b32 v134, v60, v52 offset0:40 offset1:44
	ds_write2_b32 v134, v44, v36 offset0:48 offset1:52
	ds_write2_b32 v134, v28, v16 offset0:56 offset1:60
	s_or_b64 exec, exec, s[62:63]
	s_cmpk_eq_i32 s3, 0x100
	s_cbranch_scc1 .LBB0_1136
	s_branch .LBB0_1073
